# P5 epilogue: last-use residual (bf16 x) loads carry the nt hint
# speedup vs baseline: 1.0004x; 1.0004x over previous
;     __device__ __forceinline__ void piece(size_t row, int col, f32x4 v0, f32x4 v1, const f32x4 a0, const f32x4 a1, const f32x4 b0, const f32x4 b1, const f32x4 c0, const f32x4 c1,
;                                           float mean, float rstd, float& s, float& ss) const {
;         if constexpr (MODE == 1) { f32x4 r0, r1; unpack8(*(const u32x4*)(Tin + row * DM + col), r0, r1); v0 = r0 * ALPHA + v0; v1 = r1 * ALPHA + v1; }
;         if constexpr (MODE == 2) { v0 = ((v0 - a0 * mean) * rstd + b0) * scale; v1 = ((v1 - a1 * mean) * rstd + b1) * scale; }
;         if constexpr (RECOMP) { f32x4 r0, r1; unpack8(*(const u32x4*)(Tin + row * DM + col), r0, r1);
;             r0 = (r0 - mean) * rstd * a0 + b0; r1 = (r1 - mean) * rstd * a1 + b1; v0 = r0 * ALPHA + v0; v1 = r1 * ALPHA + v1;
;             if constexpr (MODE == 5) { v0 = v0 + c0; v1 = v1 + c1; } }
;         if constexpr (MODE == 4) { v0 = (v0 - a0 * mean) * rstd + b0; v1 = (v1 - a1 * mean) * rstd + b1;
; #pragma unroll
;             for (int e = 0; e < 4; ++e) { const float x = fmaxf(v0[e], 0.f), y = fmaxf(v1[e], 0.f); v0[e] = x * x; v1[e] = y * y; } }
;         if constexpr (PROD) {
; #pragma unroll
;             for (int e = 0; e < 4; ++e) { s += v0[e] + v1[e]; ss += v0[e] * v0[e] + v1[e] * v1[e]; } }
;         if constexpr (MODE == 5) { float* o = (float*)O + row * ldo + col; *(f32x4*)o = v0; *(f32x4*)(o + 4) = v1; }
;         else *(u32x4*)((bf16_t*)O + row * ldo + col) = pack8(v0, v1);
;     __device__ __forceinline__ void operator()(const f32x4 (&acc)[2][2][4][2], const Unit& u, int wr, int wc, int fr_, int fq_, LAS unsigned char* ldsx) const {
;     ...
;         EPI_FOR_ROWS {
;             const int rl = ai * HALF + wr * 64 + m * 16 + fr; const size_t row = (size_t)u.row0 + rl;
;             float mean = 0.f, rstd = 0.f; if constexpr (CONS) { const f32x2 st = X[rl]; mean = st.x; rstd = st.y; }
;             float s = 0.f, ss = 0.f;
; #pragma unroll
;             for (int bj = 0; bj < 2; ++bj) piece(row, colb + bj * HALF, acc[ai][bj][m][0], acc[ai][bj][m][1], av[bj][0], av[bj][1], bv[bj][0], bv[bj][1], cv[bj][0], cv[bj][1], mean, rstd, s, ss);
;             if constexpr (PROD) { s += __shfl_xor(s, 16); ss += __shfl_xor(ss, 16); s += __shfl_xor(s, 32); ss += __shfl_xor(ss, 32);
;                 if (fq == 0) st_out[row * 16 + (u.col0 >> 8) * 4 + wc] = (f32x2){s, ss}; }
.LBB0_824:
	v_mov_b32_e32 v145, v150
	v_mov_b32_e32 v157, v151
	s_add_i32 s1, s0, s65
	v_add_u32_e32 v146, s64, v145
	s_ashr_i32 s21, s20, 31
	v_ashrrev_i32_e32 v147, 31, v146
	v_lshl_add_u32 v144, v157, 3, s1
	v_lshl_add_u64 v[148:149], v[146:147], 0, s[20:21]
	v_lshlrev_b64 v[166:167], 11, v[148:149]
	v_ashrrev_i32_e32 v145, 31, v144
	v_lshl_add_u64 v[158:159], s[44:45], 0, v[166:167]
	v_lshlrev_b64 v[144:145], 1, v[144:145]
	v_lshl_add_u64 v[162:163], v[158:159], 0, v[144:145]
	global_load_dwordx4 v[158:161], v[162:163], off nt
	s_nop 0
	global_load_dwordx4 v[162:165], v[162:163], off offset:256 nt
	v_and_b32_e32 v168, 64, v156
	s_ashr_i32 s0, s0, 6
	v_xor_b32_e32 v147, 16, v156
	v_add_u32_e32 v168, 64, v168
	v_xor_b32_e32 v169, 32, v156
	s_and_b32 s36, s0, -4
	v_cmp_lt_i32_e64 s[0:1], v147, v168
	v_cmp_eq_u32_e32 vcc, 0, v157
	v_lshl_add_u64 v[166:167], s[60:61], 0, v[166:167]
	v_cndmask_b32_e64 v147, v156, v147, s[0:1]
	v_cmp_lt_i32_e64 s[0:1], v169, v168
	v_lshlrev_b32_e32 v157, 2, v147
	v_lshl_add_u64 v[166:167], v[166:167], 0, v[144:145]
	v_cndmask_b32_e64 v168, v156, v169, s[0:1]
	v_lshlrev_b32_e32 v147, 2, v168
	s_ashr_i32 s37, s36, 31
	v_add_u32_e32 v244, 16, v146
	v_ashrrev_i32_e32 v245, 31, v244
	v_lshl_add_u64 v[244:245], v[244:245], 0, s[20:21]
	v_lshlrev_b64 v[244:245], 11, v[244:245]
	v_lshl_add_u64 v[244:245], s[44:45], 0, v[244:245]
	v_lshl_add_u64 v[244:245], v[244:245], 0, v[144:145]
	global_load_dwordx4 v[184:187], v[244:245], off nt
	global_load_dwordx4 v[188:191], v[244:245], off offset:256 nt
	v_add_u32_e32 v244, 32, v146
	v_ashrrev_i32_e32 v245, 31, v244
	v_lshl_add_u64 v[244:245], v[244:245], 0, s[20:21]
	v_lshlrev_b64 v[244:245], 11, v[244:245]
	v_lshl_add_u64 v[244:245], s[44:45], 0, v[244:245]
	v_lshl_add_u64 v[244:245], v[244:245], 0, v[144:145]
	global_load_dwordx4 v[192:195], v[244:245], off nt
	global_load_dwordx4 v[196:199], v[244:245], off offset:256 nt
	v_add_u32_e32 v244, 48, v146
	v_ashrrev_i32_e32 v245, 31, v244
	v_lshl_add_u64 v[244:245], v[244:245], 0, s[20:21]
	v_lshlrev_b64 v[244:245], 11, v[244:245]
	v_lshl_add_u64 v[244:245], s[44:45], 0, v[244:245]
	v_lshl_add_u64 v[244:245], v[244:245], 0, v[144:145]
	global_load_dwordx4 v[204:207], v[244:245], off nt
	global_load_dwordx4 v[208:211], v[244:245], off offset:256 nt
	v_add_u32_e32 v244, 0x80, v146
	v_ashrrev_i32_e32 v245, 31, v244
	v_lshl_add_u64 v[244:245], v[244:245], 0, s[20:21]
	v_lshlrev_b64 v[244:245], 11, v[244:245]
	v_lshl_add_u64 v[244:245], s[44:45], 0, v[244:245]
	v_lshl_add_u64 v[244:245], v[244:245], 0, v[144:145]
	global_load_dwordx4 v[212:215], v[244:245], off nt
	global_load_dwordx4 v[216:219], v[244:245], off offset:256 nt
	v_add_u32_e32 v244, 0x90, v146
	v_ashrrev_i32_e32 v245, 31, v244
	v_lshl_add_u64 v[244:245], v[244:245], 0, s[20:21]
	v_lshlrev_b64 v[244:245], 11, v[244:245]
	v_lshl_add_u64 v[244:245], s[44:45], 0, v[244:245]
	v_lshl_add_u64 v[244:245], v[244:245], 0, v[144:145]
	global_load_dwordx4 v[220:223], v[244:245], off nt
	global_load_dwordx4 v[224:227], v[244:245], off offset:256 nt
	v_add_u32_e32 v244, 0xa0, v146
	v_ashrrev_i32_e32 v245, 31, v244
	v_lshl_add_u64 v[244:245], v[244:245], 0, s[20:21]
	v_lshlrev_b64 v[244:245], 11, v[244:245]
	v_lshl_add_u64 v[244:245], s[44:45], 0, v[244:245]
	v_lshl_add_u64 v[244:245], v[244:245], 0, v[144:145]
	global_load_dwordx4 v[228:231], v[244:245], off nt
	global_load_dwordx4 v[232:235], v[244:245], off offset:256 nt
	v_add_u32_e32 v244, 0xb0, v146
	v_ashrrev_i32_e32 v245, 31, v244
	v_lshl_add_u64 v[244:245], v[244:245], 0, s[20:21]
	v_lshlrev_b64 v[244:245], 11, v[244:245]
	v_lshl_add_u64 v[244:245], s[44:45], 0, v[244:245]
	v_lshl_add_u64 v[244:245], v[244:245], 0, v[144:145]
	global_load_dwordx4 v[236:239], v[244:245], off nt
	global_load_dwordx4 v[240:243], v[244:245], off offset:256 nt
	s_waitcnt vmcnt(14)
; __device__ __forceinline__ u32x4 pack8(const f32x4 a, const f32x4 b) { u32x4 w; w.x = cvt_pk_bf16(a[0], a[1]); w.y = cvt_pk_bf16(a[2], a[3]); w.z = cvt_pk_bf16(b[0], b[1]); w.w = cvt_pk_bf16(b[2], b[3]); return w; }
;     __device__ __forceinline__ void piece(size_t row, int col, f32x4 v0, f32x4 v1, const f32x4 a0, const f32x4 a1, const f32x4 b0, const f32x4 b1, const f32x4 c0, const f32x4 c1,
;                                           float mean, float rstd, float& s, float& ss) const {
;     ...
;         if constexpr (PROD) {
; #pragma unroll
;             for (int e = 0; e < 4; ++e) { s += v0[e] + v1[e]; ss += v0[e] * v0[e] + v1[e] * v1[e]; } }
;         if constexpr (MODE == 5) { float* o = (float*)O + row * ldo + col; *(f32x4*)o = v0; *(f32x4*)(o + 4) = v1; }
;         else *(u32x4*)((bf16_t*)O + row * ldo + col) = pack8(v0, v1);
;     __device__ __forceinline__ void operator()(const f32x4 (&acc)[2][2][4][2], const Unit& u, int wr, int wc, int fr_, int fq_, LAS unsigned char* ldsx) const {
;     ...
;             if constexpr (PROD) { s += __shfl_xor(s, 16); ss += __shfl_xor(ss, 16); s += __shfl_xor(s, 32); ss += __shfl_xor(ss, 32);
;                 if (fq == 0) st_out[row * 16 + (u.col0 >> 8) * 4 + wc] = (f32x2){s, ss}; }
	v_lshlrev_b32_e32 v168, 16, v158
	v_and_b32_e32 v169, 0xffff0000, v158
	v_lshlrev_b32_e32 v170, 16, v160
	v_and_b32_e32 v171, 0xffff0000, v160
	v_lshlrev_b32_e32 v158, 16, v159
	v_and_b32_e32 v159, 0xffff0000, v159
	v_lshlrev_b32_e32 v160, 16, v161
	v_and_b32_e32 v161, 0xffff0000, v161
	v_lshlrev_b32_e32 v172, 16, v162
	v_and_b32_e32 v173, 0xffff0000, v162
	v_lshlrev_b32_e32 v162, 16, v163
	v_and_b32_e32 v163, 0xffff0000, v163
	v_lshlrev_b32_e32 v174, 16, v164
	v_and_b32_e32 v175, 0xffff0000, v164
	v_lshlrev_b32_e32 v164, 16, v165
	v_and_b32_e32 v165, 0xffff0000, v165
	v_pk_fma_f32 v[124:125], v[168:169], s[24:25], v[124:125] op_sel_hi:[1,0,1]
	v_pk_fma_f32 v[120:121], v[170:171], s[24:25], v[120:121] op_sel_hi:[1,0,1]
	v_pk_fma_f32 v[126:127], v[158:159], s[24:25], v[126:127] op_sel_hi:[1,0,1]
	v_pk_fma_f32 v[122:123], v[160:161], s[24:25], v[122:123] op_sel_hi:[1,0,1]
	v_pk_fma_f32 v[118:119], v[162:163], s[24:25], v[118:119] op_sel_hi:[1,0,1]
	v_pk_fma_f32 v[158:159], v[164:165], s[24:25], v[114:115] op_sel_hi:[1,0,1]
	v_pk_add_f32 v[162:163], v[124:125], v[120:121]
	v_pk_mul_f32 v[164:165], v[120:121], v[120:121]
	v_pk_fma_f32 v[160:161], v[174:175], s[24:25], v[112:113] op_sel_hi:[1,0,1]
	v_pk_mul_f32 v[168:169], v[122:123], v[122:123]
	v_cvt_pk_bf16_f32 v112, v124, v125
	v_add_f32_e32 v162, 0, v162
	v_pk_fma_f32 v[124:125], v[124:125], v[124:125], v[164:165]
	v_pk_fma_f32 v[116:117], v[172:173], s[24:25], v[116:117] op_sel_hi:[1,0,1]
	v_pk_add_f32 v[114:115], v[126:127], v[122:123]
	v_cvt_pk_bf16_f32 v113, v126, v127
	v_pk_fma_f32 v[126:127], v[126:127], v[126:127], v[168:169]
	v_add_f32_e32 v162, v163, v162
	v_add_f32_e32 v124, v125, v124
	v_pk_mul_f32 v[172:173], v[116:117], v[116:117]
	v_add_f32_e32 v114, v114, v162
	v_add_f32_e32 v124, v126, v124
	v_pk_add_f32 v[170:171], v[116:117], v[160:161]
	v_pk_fma_f32 v[164:165], v[160:161], v[160:161], v[172:173]
	v_add_f32_e32 v114, v115, v114
	v_add_f32_e32 v115, v127, v124
	v_mov_b32_e32 v174, v118
	v_mov_b32_e32 v175, v158
	v_mul_f32_e32 v176, v118, v118
	v_mul_f32_e32 v177, v159, v159
	v_add_f32_e32 v124, v114, v170
	v_add_f32_e32 v114, v115, v164
	v_pk_add_f32 v[178:179], v[118:119], v[158:159]
	v_pk_mul_f32 v[180:181], v[118:119], v[118:119]
	v_pk_fma_f32 v[168:169], v[174:175], v[174:175], v[176:177] op_sel_hi:[1,1,0]
	v_pk_add_f32 v[114:115], v[164:165], v[114:115] op_sel_hi:[1,0]
	v_mov_b32_e32 v179, v181
	v_mov_b32_e32 v168, v119
	v_add_f32_e32 v176, v171, v124
	v_mov_b32_e32 v114, v159
	v_pk_add_f32 v[124:125], v[178:179], v[176:177]
	v_pk_add_f32 v[114:115], v[168:169], v[114:115]
	v_cvt_pk_bf16_f32 v116, v116, v117
	v_cvt_pk_bf16_f32 v117, v118, v119
	v_cvt_pk_bf16_f32 v118, v160, v161
	v_cvt_pk_bf16_f32 v119, v158, v159
	global_store_dwordx4 v[166:167], v[116:119], off offset:256
	v_pk_add_f32 v[124:125], v[124:125], v[114:115]
	ds_bpermute_b32 v126, v157, v124
	ds_bpermute_b32 v127, v157, v125
	v_cvt_pk_bf16_f32 v114, v120, v121
	v_cvt_pk_bf16_f32 v115, v122, v123
	global_store_dwordx4 v[166:167], v[112:115], off
	s_waitcnt lgkmcnt(0)
	s_nop 0
	v_pk_add_f32 v[112:113], v[124:125], v[126:127]
	ds_bpermute_b32 v114, v147, v112
	ds_bpermute_b32 v115, v147, v113
	s_and_saveexec_b64 s[0:1], vcc
	s_cbranch_execz .LBB0_826
	s_waitcnt lgkmcnt(0)
	v_pk_add_f32 v[112:113], v[112:113], v[114:115]
	v_lshlrev_b64 v[114:115], 7, v[148:149]
	v_lshl_add_u64 v[114:115], s[14:15], 0, v[114:115]
	v_lshl_add_u64 v[114:115], s[36:37], 3, v[114:115]
	s_lshl_b32 s10, s43, 3
	v_lshl_add_u64 v[114:115], v[114:115], 0, s[10:11]
	global_store_dwordx2 v[114:115], v[112:113], off
